# in_proj: adjacent-halves weight-row permutation + EpiProj stores as 8 rows x 128 B via DPP row_ror:8 exchange
# baseline (speedup 1.0000x reference)
.LBB0_916:
	v_ashrrev_i32_e32 v0, 31, v207
	v_lshrrev_b32_e32 v0, 26, v0
	v_add_u32_e32 v0, v207, v0
	v_ashrrev_i32_e32 v12, 6, v0
	v_bfe_i32 v0, v207, 27, 1
	v_lshlrev_b32_e32 v1, 4, v207
	v_lshrrev_b32_e32 v0, 22, v0
	v_add_u32_e32 v0, v1, v0
	v_and_b32_e32 v0, 0xfffffc00, v0
	v_sub_u32_e32 v0, v1, v0
	v_lshrrev_b32_e32 v2, 4, v0
	v_bitop3_b32 v0, v2, v0, 32 bitop3:0x6c
	v_ashrrev_i32_e32 v4, 31, v0
	v_lshrrev_b32_e32 v4, 26, v4
	v_add_u32_e32 v4, v0, v4
	s_ashr_i32 s0, s3, 3
	v_readlane_b32 s3, v255, 2
	v_lshlrev_b32_e32 v2, 3, v12
	v_ashrrev_i32_e32 v13, 6, v4
	v_and_b32_e32 v4, 0xc0, v4
	s_mul_hi_i32 s1, s3, 0x688000
	s_mul_i32 s3, s3, 0x688000
	v_and_b32_e32 v2, -16, v2
	v_sub_u32_e32 v0, v0, v4
	s_add_u32 s26, s72, s3
	v_add_u32_e32 v2, v13, v2
	v_ashrrev_i16_sdwa v0, v190, sext(v0) dst_sel:DWORD dst_unused:UNUSED_PAD src0_sel:DWORD src1_sel:BYTE_0
	s_addc_u32 s27, s73, s1
	v_lshlrev_b32_e32 v5, 5, v12
	v_bfe_i32 v14, v0, 0, 16
	v_lshlrev_b32_e32 v0, 1, v2
	v_lshrrev_b32_e32 v4, 2, v2
	v_and_b32_e32 v6, 3, v13
	s_mov_b32 s1, 0x1fffe0
	v_and_b32_e32 v5, 32, v5
	v_and_b32_e32 v0, 24, v0
	v_and_b32_e32 v4, 4, v4
	v_and_or_b32 v6, v2, s1, v6
	v_or3_b32 v4, v6, v4, v0
	v_add_lshl_u32 v5, v5, v14, 1
	v_add_u32_e32 v1, 0x2000, v1
	v_and_b32_e32 v20, 0x1fffe0, v2
	v_lshl_add_u32 v0, v2, 11, v5
	v_lshl_add_u32 v2, v4, 11, v5
	v_lshl_add_u32 v2, v20, 11, v2
	v_ashrrev_i32_e32 v4, 31, v1
	v_lshrrev_b32_e32 v4, 22, v4
	v_add_u32_e32 v4, v1, v4
	v_ashrrev_i32_e32 v15, 10, v4
	v_mul_i32_i24_e32 v4, 0x400, v15
	v_sub_u32_e32 v1, v1, v4
	v_lshrrev_b32_e32 v4, 4, v1
	v_bitop3_b32 v1, v4, v1, 32 bitop3:0x6c
	v_ashrrev_i32_e32 v5, 31, v1
	v_lshrrev_b32_e32 v5, 26, v5
	v_lshlrev_b32_e32 v4, 3, v15
	v_add_u32_e32 v5, v1, v5
	v_and_b32_e32 v4, -16, v4
	v_ashrrev_i32_e32 v16, 6, v5
	v_add_u32_e32 v4, v16, v4
	v_and_b32_e32 v21, 0x1fffe0, v4
	v_and_b32_e32 v7, 3, v16
	s_add_i32 s0, s2, s0
	v_and_b32_e32 v5, 0xc0, v5
	v_and_or_b32 v7, v4, s1, v7
	s_mul_hi_i32 s1, s0, 0x4ec4ec4f
	v_sub_u32_e32 v1, v1, v5
	s_lshr_b32 s2, s1, 31
	s_ashr_i32 s1, s1, 5
	v_ashrrev_i16_sdwa v1, v190, sext(v1) dst_sel:DWORD dst_unused:UNUSED_PAD src0_sel:DWORD src1_sel:BYTE_0
	s_add_i32 s1, s1, s2
	v_lshlrev_b32_e32 v6, 5, v15
	v_bfe_i32 v17, v1, 0, 16
	v_lshlrev_b32_e32 v1, 1, v4
	v_lshrrev_b32_e32 v5, 2, v4
	s_lshl_b32 s6, s1, 3
	v_and_b32_e32 v6, 32, v6
	v_and_b32_e32 v1, 24, v1
	v_and_b32_e32 v5, 4, v5
	s_sub_i32 s2, 0x82, s6
	v_or3_b32 v1, v7, v5, v1
	v_add_lshl_u32 v5, v6, v17, 1
	s_min_u32 s7, s2, 8
	s_mulk_i32 s1, 0x68
	v_lshl_add_u32 v140, v4, 11, v5
	s_sub_i32 s10, s0, s1
	v_cvt_f32_ubyte0_e32 v4, s7
	v_lshl_add_u32 v142, v1, 11, v5
	v_lshl_add_u32 v142, v21, 11, v142
	v_cvt_f32_i32_e32 v1, s10
	v_rcp_iflag_f32_e32 v5, v4
	s_ashr_i32 s3, s4, 6
	s_ashr_i32 s0, s10, 30
	s_ashr_i32 s5, s4, 8
	v_mul_f32_e32 v5, v1, v5
	v_trunc_f32_e32 v5, v5
	v_fma_f32 v1, -v5, v4, v1
	v_cvt_i32_f32_e32 v5, v5
	s_lshl_b32 s28, s3, 10
	s_or_b32 s2, s0, 1
	v_cmp_ge_f32_e64 s[0:1], |v1|, v4
	s_and_b64 s[0:1], s[0:1], exec
	s_cselect_b32 s0, s2, 0
	v_readfirstlane_b32 s1, v5
	s_add_i32 s2, s1, s0
	s_mul_i32 s0, s2, s7
	s_sub_i32 s0, s10, s0
	s_sext_i32_i8 s0, s0
	s_add_i32 s16, s6, s0
	s_ashr_i32 s17, s16, 31
	s_bfe_i64 s[6:7], s[2:3], 0x80000
	s_lshl_b64 s[0:1], s[16:17], 19
	s_lshl_b64 s[6:7], s[6:7], 19
	s_add_u32 s42, s26, s6
	s_addc_u32 s43, s27, s7
	s_add_i32 s29, s28, 0
	s_add_i32 m0, s29, 0x10000
	v_mov_b32_e32 v143, v3
	global_load_lds_dwordx4 v2, s[42:43]
	s_add_i32 m0, s29, 0x12000
	s_add_u32 s6, s42, 0x10000
	global_load_lds_dwordx4 v142, s[42:43]
	s_addc_u32 s7, s43, 0
	s_add_i32 m0, s29, 0x14000
	v_mov_b32_e32 v1, v3
	global_load_lds_dwordx4 v2, s[6:7]
	s_add_i32 m0, s29, 0x16000
	s_add_u32 s22, s20, s0
	s_addc_u32 s23, s21, s1
	s_add_i32 s44, s29, 0x2000
	global_load_lds_dwordx4 v142, s[6:7]
	s_mov_b32 m0, s29
	s_add_u32 s0, s22, 0x40000
	global_load_lds_dwordx4 v0, s[22:23]
	s_mov_b32 m0, s44
	s_addc_u32 s1, s23, 0
	s_add_i32 s45, s29, 0x4000
	global_load_lds_dwordx4 v140, s[22:23]
	s_mov_b32 m0, s45
	s_add_i32 s46, s29, 0x6000
	global_load_lds_dwordx4 v0, s[0:1]
	s_mov_b32 m0, s46
	v_mov_b32_e32 v141, v3
	global_load_lds_dwordx4 v140, s[0:1]
	s_cmp_eq_u32 s5, 1
	v_lshl_add_u64 v[10:11], s[42:43], 0, v[2:3]
	s_waitcnt lgkmcnt(0)
	v_lshl_add_u64 v[8:9], s[42:43], 0, v[142:143]
	v_lshl_add_u64 v[4:5], s[22:23], 0, v[0:1]
	s_cselect_b64 s[0:1], -1, 0
	s_cmp_lg_u32 s5, 1
	v_lshl_add_u64 v[6:7], s[22:23], 0, v[140:141]
	s_cbranch_scc1 .LBB0_918
	s_barrier
.LBB0_918:
	s_and_b32 s3, s3, 3
	s_add_i32 m0, s29, 0x18000
	v_lshl_add_u64 v[10:11], v[10:11], 0, s[92:93]
	s_lshl_b32 s10, s5, 13
	s_lshl_b32 s11, s3, 12
	s_waitcnt vmcnt(2)
	s_barrier
	global_load_lds_dwordx4 v[10:11], off
	v_lshl_add_u64 v[8:9], v[8:9], 0, s[92:93]
	s_add_i32 m0, s29, 0x1a000
	s_add_i32 s47, s29, 0x8000
	s_add_i32 s48, s29, 0xa000
	global_load_lds_dwordx4 v[8:9], off
	v_lshl_add_u64 v[4:5], v[4:5], 0, s[92:93]
	s_mov_b32 m0, s47
	s_add_u32 s6, s42, 0x10080
	global_load_lds_dwordx4 v[4:5], off
	v_lshl_add_u64 v[4:5], v[6:7], 0, s[92:93]
	s_mov_b32 m0, s48
	s_addc_u32 s7, s43, 0
	global_load_lds_dwordx4 v[4:5], off
	s_add_i32 m0, s29, 0x1c000
	v_lshl_add_u64 v[4:5], s[6:7], 0, v[2:3]
	global_load_lds_dwordx4 v[4:5], off
	v_lshl_add_u64 v[4:5], s[6:7], 0, v[142:143]
	s_add_i32 m0, s29, 0x1e000
	s_cmpk_lt_u32 s4, 0x100
	global_load_lds_dwordx4 v[4:5], off
	v_bfe_u32 v5, v207, 4, 2
	v_lshlrev_b32_e32 v6, 3, v5
	s_sext_i32_i8 s12, s2
	v_lshl_or_b32 v153, s3, 6, v6
	s_cselect_b64 s[2:3], -1, 0
	s_and_b32 s4, s4, 0xc0
	v_or_b32_e32 v154, s4, v138
	v_readlane_b32 s4, v254, 32
	v_and_b32_e32 v4, 15, v207
	v_lshlrev_b32_e32 v5, 4, v5
	s_ashr_i32 s49, s4, 31
	v_readlane_b32 s6, v254, 18
	s_lshl_b32 s4, s5, 8
	v_lshl_or_b32 v137, s5, 6, v4
	v_lshl_or_b32 v5, v4, 6, v5
	v_lshlrev_b32_e32 v4, 2, v4
	s_add_i32 s4, s6, s4
	v_and_b32_e32 v7, 32, v4
	v_add_u32_e32 v156, s4, v4
	v_lshlrev_b32_e32 v4, 14, v12
	v_and_b32_e32 v4, 0xffff8000, v4
	v_bitop3_b32 v8, v5, s10, v7 bitop3:0xde
	v_bitop3_b32 v152, s11, v5, v7 bitop3:0xf6
	v_lshl_add_u32 v4, v13, 11, v4
	v_and_b32_e32 v5, 1, v12
	v_lshl_or_b32 v4, v5, 6, v4
	v_lshl_add_u32 v144, v14, 1, v4
	v_lshlrev_b32_e32 v4, 14, v15
	v_and_b32_e32 v4, 0xffff8000, v4
	s_waitcnt vmcnt(6)
	v_lshl_add_u32 v4, v16, 11, v4
	v_and_b32_e32 v5, 1, v15
	v_lshl_or_b32 v4, v5, 6, v4
	v_lshl_add_u32 v155, v154, 2, s6
	v_mov_b32_e32 v145, v3
	v_lshl_add_u32 v146, v17, 1, v4
	v_mov_b32_e32 v147, v3
	s_mov_b32 s50, 0
	v_add_u32_e32 v157, 0, v8
	s_barrier
	s_branch .LBB0_921

.LBB0_928:
	s_add_u32 s18, s40, 0xfffc0080
	s_addc_u32 s19, s41, -1
	s_add_i32 s52, 0, 0x10000
	s_cmp_eq_u32 s51, 12
	s_cselect_b32 s25, s7, s19
	s_cselect_b32 s24, s13, s18
	s_cselect_b32 s23, s5, s43
	s_cselect_b32 s22, s17, s42
	s_add_i32 s53, 0, 0x14000
	v_add_u32_e32 v166, s52, v152
	v_add_u32_e32 v182, s53, v152
	ds_read_b128 v[148:151], v166
	ds_read_b128 v[158:161], v166 offset:1024
	ds_read_b128 v[162:165], v166 offset:2048
	ds_read_b128 v[166:169], v166 offset:3072
	ds_read_b128 v[170:173], v182
	ds_read_b128 v[174:177], v182 offset:1024
	ds_read_b128 v[178:181], v182 offset:2048
	ds_read_b128 v[182:185], v182 offset:3072
	v_lshl_add_u64 v[236:237], s[40:41], 0, v[144:145]
	s_add_i32 m0, s29, 0xc000
	ds_read_b128 v[186:189], v157
	ds_read_b128 v[208:211], v157 offset:1024
	ds_read_b128 v[212:215], v157 offset:2048
	ds_read_b128 v[216:219], v157 offset:3072
	ds_read_b128 v[220:223], v157 offset:4096
	ds_read_b128 v[224:227], v157 offset:5120
	ds_read_b128 v[228:231], v157 offset:6144
	ds_read_b128 v[232:235], v157 offset:7168
	global_load_lds_dwordx4 v[236:237], off
	v_lshl_add_u64 v[236:237], s[40:41], 0, v[146:147]
	s_add_i32 m0, s29, 0xe000
	s_nop 0
	global_load_lds_dwordx4 v[236:237], off
	s_waitcnt vmcnt(8)
	s_waitcnt lgkmcnt(0)
	s_barrier
	s_setprio 1
	s_waitcnt lgkmcnt(0)
	v_mfma_f32_16x16x32_bf16 v[128:131], v[148:151], v[186:189], v[128:131]
	v_mfma_f32_16x16x32_bf16 v[124:127], v[162:165], v[186:189], v[124:127]
	v_mfma_f32_16x16x32_bf16 v[116:119], v[148:151], v[212:215], v[116:119]
	v_mfma_f32_16x16x32_bf16 v[108:111], v[162:165], v[212:215], v[108:111]
	v_mfma_f32_16x16x32_bf16 v[100:103], v[148:151], v[220:223], v[100:103]
	v_mfma_f32_16x16x32_bf16 v[92:95], v[162:165], v[220:223], v[92:95]
	v_mfma_f32_16x16x32_bf16 v[84:87], v[148:151], v[228:231], v[84:87]
	v_mfma_f32_16x16x32_bf16 v[76:79], v[162:165], v[228:231], v[76:79]
	v_mfma_f32_16x16x32_bf16 v[128:131], v[158:161], v[208:211], v[128:131]
	v_mfma_f32_16x16x32_bf16 v[124:127], v[166:169], v[208:211], v[124:127]
	v_mfma_f32_16x16x32_bf16 v[116:119], v[158:161], v[216:219], v[116:119]
	v_mfma_f32_16x16x32_bf16 v[108:111], v[166:169], v[216:219], v[108:111]
	v_mfma_f32_16x16x32_bf16 v[100:103], v[158:161], v[224:227], v[100:103]
	v_mfma_f32_16x16x32_bf16 v[92:95], v[166:169], v[224:227], v[92:95]
	v_mfma_f32_16x16x32_bf16 v[84:87], v[158:161], v[232:235], v[84:87]
	v_mfma_f32_16x16x32_bf16 v[76:79], v[166:169], v[232:235], v[76:79]
	s_setprio 0
	s_setprio 1
	v_mfma_f32_16x16x32_bf16 v[120:123], v[170:173], v[186:189], v[120:123]
	v_mfma_f32_16x16x32_bf16 v[112:115], v[178:181], v[186:189], v[112:115]
	v_mfma_f32_16x16x32_bf16 v[104:107], v[170:173], v[212:215], v[104:107]
	v_mfma_f32_16x16x32_bf16 v[96:99], v[178:181], v[212:215], v[96:99]
	v_mfma_f32_16x16x32_bf16 v[88:91], v[170:173], v[220:223], v[88:91]
	v_mfma_f32_16x16x32_bf16 v[80:83], v[178:181], v[220:223], v[80:83]
	v_mfma_f32_16x16x32_bf16 v[72:75], v[170:173], v[228:231], v[72:75]
	v_mfma_f32_16x16x32_bf16 v[68:71], v[178:181], v[228:231], v[68:71]
	v_mfma_f32_16x16x32_bf16 v[120:123], v[174:177], v[208:211], v[120:123]
	v_mfma_f32_16x16x32_bf16 v[112:115], v[182:185], v[208:211], v[112:115]
	v_mfma_f32_16x16x32_bf16 v[104:107], v[174:177], v[216:219], v[104:107]
	v_mfma_f32_16x16x32_bf16 v[96:99], v[182:185], v[216:219], v[96:99]
	v_mfma_f32_16x16x32_bf16 v[88:91], v[174:177], v[224:227], v[88:91]
	v_mfma_f32_16x16x32_bf16 v[80:83], v[182:185], v[224:227], v[80:83]
	v_mfma_f32_16x16x32_bf16 v[72:75], v[174:177], v[232:235], v[72:75]
	v_mfma_f32_16x16x32_bf16 v[68:71], v[182:185], v[232:235], v[68:71]
	s_setprio 0
	s_barrier
	s_add_i32 s18, s52, s28
	v_lshl_add_u64 v[236:237], s[22:23], 0, v[2:3]
	s_mov_b32 m0, s18
	ds_read_b128 v[186:189], v157 offset:16384
	ds_read_b128 v[208:211], v157 offset:17408
	ds_read_b128 v[212:215], v157 offset:18432
	ds_read_b128 v[216:219], v157 offset:19456
	ds_read_b128 v[220:223], v157 offset:20480
	ds_read_b128 v[224:227], v157 offset:21504
	ds_read_b128 v[228:231], v157 offset:22528
	ds_read_b128 v[232:235], v157 offset:23552
	global_load_lds_dwordx4 v[236:237], off
	s_add_i32 m0, s18, 0x2000
	s_add_u32 s18, s22, 0x10000
	v_lshl_add_u64 v[238:239], s[22:23], 0, v[142:143]
	s_addc_u32 s19, s23, 0
	s_add_i32 s52, s53, s28
	global_load_lds_dwordx4 v[238:239], off
	v_lshl_add_u64 v[240:241], s[18:19], 0, v[2:3]
	s_mov_b32 m0, s52
	v_lshl_add_u64 v[242:243], s[24:25], 0, v[140:141]
	global_load_lds_dwordx4 v[240:241], off
	v_lshl_add_u64 v[240:241], s[18:19], 0, v[142:143]
	s_add_i32 m0, s52, 0x2000
	s_nop 0
	global_load_lds_dwordx4 v[240:241], off
	v_lshl_add_u64 v[240:241], s[24:25], 0, v[0:1]
	s_mov_b32 m0, s29
	s_nop 0
	global_load_lds_dwordx4 v[240:241], off
	s_mov_b32 m0, s44
	s_nop 0
	global_load_lds_dwordx4 v[242:243], off
	s_waitcnt vmcnt(8)
	s_waitcnt lgkmcnt(0)
	s_barrier
	s_setprio 1
	s_waitcnt lgkmcnt(0)
	v_mfma_f32_16x16x32_bf16 v[64:67], v[148:151], v[186:189], v[64:67]
	v_mfma_f32_16x16x32_bf16 v[60:63], v[162:165], v[186:189], v[60:63]
	v_mfma_f32_16x16x32_bf16 v[52:55], v[148:151], v[212:215], v[52:55]
	v_mfma_f32_16x16x32_bf16 v[44:47], v[162:165], v[212:215], v[44:47]
	v_mfma_f32_16x16x32_bf16 v[36:39], v[148:151], v[220:223], v[36:39]
	v_mfma_f32_16x16x32_bf16 v[28:31], v[162:165], v[220:223], v[28:31]
	v_mfma_f32_16x16x32_bf16 v[20:23], v[148:151], v[228:231], v[20:23]
	v_mfma_f32_16x16x32_bf16 v[12:15], v[162:165], v[228:231], v[12:15]
	v_mfma_f32_16x16x32_bf16 v[64:67], v[158:161], v[208:211], v[64:67]
	v_mfma_f32_16x16x32_bf16 v[60:63], v[166:169], v[208:211], v[60:63]
	v_mfma_f32_16x16x32_bf16 v[52:55], v[158:161], v[216:219], v[52:55]
	v_mfma_f32_16x16x32_bf16 v[44:47], v[166:169], v[216:219], v[44:47]
	v_mfma_f32_16x16x32_bf16 v[36:39], v[158:161], v[224:227], v[36:39]
	v_mfma_f32_16x16x32_bf16 v[28:31], v[166:169], v[224:227], v[28:31]
	v_mfma_f32_16x16x32_bf16 v[20:23], v[158:161], v[232:235], v[20:23]
	v_mfma_f32_16x16x32_bf16 v[12:15], v[166:169], v[232:235], v[12:15]
	s_setprio 0
	s_setprio 1
	v_mfma_f32_16x16x32_bf16 v[56:59], v[170:173], v[186:189], v[56:59]
	v_mfma_f32_16x16x32_bf16 v[48:51], v[178:181], v[186:189], v[48:51]
	v_mfma_f32_16x16x32_bf16 v[40:43], v[170:173], v[212:215], v[40:43]
	v_mfma_f32_16x16x32_bf16 v[32:35], v[178:181], v[212:215], v[32:35]
	v_mfma_f32_16x16x32_bf16 v[24:27], v[170:173], v[220:223], v[24:27]
	v_mfma_f32_16x16x32_bf16 v[16:19], v[178:181], v[220:223], v[16:19]
	v_mfma_f32_16x16x32_bf16 v[8:11], v[170:173], v[228:231], v[8:11]
	v_mfma_f32_16x16x32_bf16 v[4:7], v[178:181], v[228:231], v[4:7]
	v_mfma_f32_16x16x32_bf16 v[56:59], v[174:177], v[208:211], v[56:59]
	v_mfma_f32_16x16x32_bf16 v[48:51], v[182:185], v[208:211], v[48:51]
	v_mfma_f32_16x16x32_bf16 v[40:43], v[174:177], v[216:219], v[40:43]
	v_mfma_f32_16x16x32_bf16 v[32:35], v[182:185], v[216:219], v[32:35]
	v_mfma_f32_16x16x32_bf16 v[24:27], v[174:177], v[224:227], v[24:27]
	v_mfma_f32_16x16x32_bf16 v[16:19], v[182:185], v[224:227], v[16:19]
	v_mfma_f32_16x16x32_bf16 v[8:11], v[174:177], v[232:235], v[8:11]
	v_mfma_f32_16x16x32_bf16 v[4:7], v[182:185], v[232:235], v[4:7]
	s_setprio 0
	s_barrier
	s_add_i32 s52, 0, 0x18000
	s_add_i32 s53, 0, 0x1c000
	v_add_u32_e32 v166, s52, v152
	v_add_u32_e32 v182, s53, v152
	ds_read_b128 v[148:151], v166
	ds_read_b128 v[158:161], v166 offset:1024
	ds_read_b128 v[162:165], v166 offset:2048
	ds_read_b128 v[166:169], v166 offset:3072
	ds_read_b128 v[170:173], v182
	ds_read_b128 v[174:177], v182 offset:1024
	ds_read_b128 v[178:181], v182 offset:2048
	ds_read_b128 v[182:185], v182 offset:3072
	s_add_u32 s18, s24, 0x40000
	s_addc_u32 s19, s25, 0
	s_mov_b32 m0, s45
	v_lshl_add_u64 v[244:245], s[18:19], 0, v[0:1]
	ds_read_b128 v[186:189], v157 offset:32768
	ds_read_b128 v[208:211], v157 offset:33792
	ds_read_b128 v[212:215], v157 offset:34816
	ds_read_b128 v[216:219], v157 offset:35840
	ds_read_b128 v[220:223], v157 offset:36864
	ds_read_b128 v[224:227], v157 offset:37888
	ds_read_b128 v[228:231], v157 offset:38912
	ds_read_b128 v[232:235], v157 offset:39936
	global_load_lds_dwordx4 v[244:245], off
	v_lshl_add_u64 v[244:245], s[18:19], 0, v[140:141]
	s_mov_b32 m0, s46
	s_nop 0
	global_load_lds_dwordx4 v[244:245], off
	s_waitcnt vmcnt(8)
	s_waitcnt lgkmcnt(0)
	s_barrier
	s_setprio 1
	s_waitcnt lgkmcnt(0)
	v_mfma_f32_16x16x32_bf16 v[128:131], v[148:151], v[186:189], v[128:131]
	v_mfma_f32_16x16x32_bf16 v[124:127], v[162:165], v[186:189], v[124:127]
	v_mfma_f32_16x16x32_bf16 v[116:119], v[148:151], v[212:215], v[116:119]
	v_mfma_f32_16x16x32_bf16 v[108:111], v[162:165], v[212:215], v[108:111]
	v_mfma_f32_16x16x32_bf16 v[100:103], v[148:151], v[220:223], v[100:103]
	v_mfma_f32_16x16x32_bf16 v[92:95], v[162:165], v[220:223], v[92:95]
	v_mfma_f32_16x16x32_bf16 v[84:87], v[148:151], v[228:231], v[84:87]
	v_mfma_f32_16x16x32_bf16 v[76:79], v[162:165], v[228:231], v[76:79]
	v_mfma_f32_16x16x32_bf16 v[128:131], v[158:161], v[208:211], v[128:131]
	v_mfma_f32_16x16x32_bf16 v[124:127], v[166:169], v[208:211], v[124:127]
	v_mfma_f32_16x16x32_bf16 v[116:119], v[158:161], v[216:219], v[116:119]
	v_mfma_f32_16x16x32_bf16 v[108:111], v[166:169], v[216:219], v[108:111]
	v_mfma_f32_16x16x32_bf16 v[100:103], v[158:161], v[224:227], v[100:103]
	v_mfma_f32_16x16x32_bf16 v[92:95], v[166:169], v[224:227], v[92:95]
	v_mfma_f32_16x16x32_bf16 v[84:87], v[158:161], v[232:235], v[84:87]
	v_mfma_f32_16x16x32_bf16 v[76:79], v[166:169], v[232:235], v[76:79]
	s_setprio 0
	s_setprio 1
	v_mfma_f32_16x16x32_bf16 v[120:123], v[170:173], v[186:189], v[120:123]
	v_mfma_f32_16x16x32_bf16 v[112:115], v[178:181], v[186:189], v[112:115]
	v_mfma_f32_16x16x32_bf16 v[104:107], v[170:173], v[212:215], v[104:107]
	v_mfma_f32_16x16x32_bf16 v[96:99], v[178:181], v[212:215], v[96:99]
	v_mfma_f32_16x16x32_bf16 v[88:91], v[170:173], v[220:223], v[88:91]
	v_mfma_f32_16x16x32_bf16 v[80:83], v[178:181], v[220:223], v[80:83]
	v_mfma_f32_16x16x32_bf16 v[72:75], v[170:173], v[228:231], v[72:75]
	v_mfma_f32_16x16x32_bf16 v[68:71], v[178:181], v[228:231], v[68:71]
	v_mfma_f32_16x16x32_bf16 v[120:123], v[174:177], v[208:211], v[120:123]
	v_mfma_f32_16x16x32_bf16 v[112:115], v[182:185], v[208:211], v[112:115]
	v_mfma_f32_16x16x32_bf16 v[104:107], v[174:177], v[216:219], v[104:107]
	v_mfma_f32_16x16x32_bf16 v[96:99], v[182:185], v[216:219], v[96:99]
	v_mfma_f32_16x16x32_bf16 v[88:91], v[174:177], v[224:227], v[88:91]
	v_mfma_f32_16x16x32_bf16 v[80:83], v[182:185], v[224:227], v[80:83]
	v_mfma_f32_16x16x32_bf16 v[72:75], v[174:177], v[232:235], v[72:75]
	v_mfma_f32_16x16x32_bf16 v[68:71], v[182:185], v[232:235], v[68:71]
	s_setprio 0
	s_barrier
	s_add_i32 s18, s52, s28
	v_lshl_add_u64 v[236:237], v[236:237], 0, s[92:93]
	s_mov_b32 m0, s18
	ds_read_b128 v[186:189], v157 offset:49152
	ds_read_b128 v[208:211], v157 offset:50176
	ds_read_b128 v[212:215], v157 offset:51200
	ds_read_b128 v[216:219], v157 offset:52224
	ds_read_b128 v[220:223], v157 offset:53248
	ds_read_b128 v[224:227], v157 offset:54272
	ds_read_b128 v[228:231], v157 offset:55296
	ds_read_b128 v[232:235], v157 offset:56320
	global_load_lds_dwordx4 v[236:237], off
	s_add_i32 m0, s18, 0x2000
	s_add_u32 s18, s22, 0x10080
	v_lshl_add_u64 v[236:237], v[238:239], 0, s[92:93]
	s_addc_u32 s19, s23, 0
	s_add_i32 s22, s53, s28
	global_load_lds_dwordx4 v[236:237], off
	v_lshl_add_u64 v[236:237], s[18:19], 0, v[2:3]
	s_mov_b32 m0, s22
	s_nop 0
	global_load_lds_dwordx4 v[236:237], off
	v_lshl_add_u64 v[236:237], s[18:19], 0, v[142:143]
	s_add_i32 m0, s22, 0x2000
	s_nop 0
	global_load_lds_dwordx4 v[236:237], off
	v_lshl_add_u64 v[236:237], v[240:241], 0, s[92:93]
	s_mov_b32 m0, s47
	s_nop 0
	global_load_lds_dwordx4 v[236:237], off
	v_lshl_add_u64 v[236:237], v[242:243], 0, s[92:93]
	s_mov_b32 m0, s48
	s_nop 0
	global_load_lds_dwordx4 v[236:237], off
	s_waitcnt vmcnt(8)
	s_waitcnt lgkmcnt(0)
	s_barrier
	s_setprio 1
	s_waitcnt lgkmcnt(0)
	v_mfma_f32_16x16x32_bf16 v[64:67], v[148:151], v[186:189], v[64:67]
	v_mfma_f32_16x16x32_bf16 v[60:63], v[162:165], v[186:189], v[60:63]
	v_mfma_f32_16x16x32_bf16 v[52:55], v[148:151], v[212:215], v[52:55]
	v_mfma_f32_16x16x32_bf16 v[44:47], v[162:165], v[212:215], v[44:47]
	v_mfma_f32_16x16x32_bf16 v[36:39], v[148:151], v[220:223], v[36:39]
	v_mfma_f32_16x16x32_bf16 v[28:31], v[162:165], v[220:223], v[28:31]
	v_mfma_f32_16x16x32_bf16 v[20:23], v[148:151], v[228:231], v[20:23]
	v_mfma_f32_16x16x32_bf16 v[12:15], v[162:165], v[228:231], v[12:15]
	v_mfma_f32_16x16x32_bf16 v[64:67], v[158:161], v[208:211], v[64:67]
	v_mfma_f32_16x16x32_bf16 v[60:63], v[166:169], v[208:211], v[60:63]
	v_mfma_f32_16x16x32_bf16 v[52:55], v[158:161], v[216:219], v[52:55]
	v_mfma_f32_16x16x32_bf16 v[44:47], v[166:169], v[216:219], v[44:47]
	v_mfma_f32_16x16x32_bf16 v[36:39], v[158:161], v[224:227], v[36:39]
	v_mfma_f32_16x16x32_bf16 v[28:31], v[166:169], v[224:227], v[28:31]
	v_mfma_f32_16x16x32_bf16 v[20:23], v[158:161], v[232:235], v[20:23]
	v_mfma_f32_16x16x32_bf16 v[12:15], v[166:169], v[232:235], v[12:15]
	s_setprio 0
	s_setprio 1
	v_mfma_f32_16x16x32_bf16 v[56:59], v[170:173], v[186:189], v[56:59]
	v_mfma_f32_16x16x32_bf16 v[48:51], v[178:181], v[186:189], v[48:51]
	v_mfma_f32_16x16x32_bf16 v[40:43], v[170:173], v[212:215], v[40:43]
	v_mfma_f32_16x16x32_bf16 v[32:35], v[178:181], v[212:215], v[32:35]
	v_mfma_f32_16x16x32_bf16 v[24:27], v[170:173], v[220:223], v[24:27]
	v_mfma_f32_16x16x32_bf16 v[16:19], v[178:181], v[220:223], v[16:19]
	v_mfma_f32_16x16x32_bf16 v[8:11], v[170:173], v[228:231], v[8:11]
	v_mfma_f32_16x16x32_bf16 v[4:7], v[178:181], v[228:231], v[4:7]
	v_mfma_f32_16x16x32_bf16 v[56:59], v[174:177], v[208:211], v[56:59]
	v_mfma_f32_16x16x32_bf16 v[48:51], v[182:185], v[208:211], v[48:51]
	v_mfma_f32_16x16x32_bf16 v[40:43], v[174:177], v[216:219], v[40:43]
	v_mfma_f32_16x16x32_bf16 v[32:35], v[182:185], v[216:219], v[32:35]
	v_mfma_f32_16x16x32_bf16 v[24:27], v[174:177], v[224:227], v[24:27]
	v_mfma_f32_16x16x32_bf16 v[16:19], v[182:185], v[224:227], v[16:19]
	v_mfma_f32_16x16x32_bf16 v[8:11], v[174:177], v[232:235], v[8:11]
	v_mfma_f32_16x16x32_bf16 v[4:7], v[182:185], v[232:235], v[4:7]
	s_setprio 0
	s_barrier
	s_add_i32 s51, s51, 2
	s_add_u32 s40, s40, 0x100
	s_addc_u32 s41, s41, 0
	s_add_u32 s42, s42, 0x100
	s_addc_u32 s43, s43, 0
	s_cmp_gt_u32 s51, 13
	s_cbranch_scc0 .LBB0_928
	s_lshl_b32 s5, s16, 8
	s_and_b64 vcc, exec, s[2:3]
	s_cbranch_vccz .LBB0_931
	v_or_b32_e32 v148, s5, v154
	v_ashrrev_i32_e32 v149, 31, v148
	v_lshlrev_b64 v[148:149], 6, v[148:149]
	v_lshl_add_u64 v[166:167], s[74:75], 0, v[148:149]
	global_load_dwordx4 v[148:151], v[166:167], off
	global_load_dwordx4 v[158:161], v[166:167], off offset:32
	global_load_dwordx4 v[162:165], v[166:167], off offset:16
	s_nop 0
	global_load_dwordx4 v[166:169], v[166:167], off offset:48
	s_barrier

.LBB0_933:
	s_waitcnt lgkmcnt(0)
	s_barrier
	ds_read_b32 v158, v156
	ds_read_b32 v160, v156 offset:64
	ds_read_b32 v162, v156 offset:128
	ds_read_b32 v164, v156 offset:192
	ds_read_b32 v166, v156 offset:512
	ds_read_b32 v168, v156 offset:576
	ds_read_b32 v170, v156 offset:640
	ds_read_b32 v172, v156 offset:704
	v_and_b32_e32 v176, 8, v137
	v_and_b32_e32 v177, -9, v137
	v_lshl_or_b32 v176, v176, 2, v153
	v_lshl_or_b32 v150, s12, 8, v176
	v_add_u32_e32 v159, s5, v177
	v_ashrrev_i32_e32 v151, 31, v150
	v_mov_b64_e32 v[148:149], s[94:95]
	v_mad_i64_i32 v[178:179], s[12:13], v159, s34, v[148:149]
	v_lshlrev_b64 v[150:151], 1, v[150:151]
	s_mov_b32 vcc_lo, 0xff00ff
	s_mov_b32 vcc_hi, 0xff00ff
	v_lshl_add_u64 v[178:179], v[178:179], 0, v[150:151]
	s_mov_b32 s12, 0xd000
	s_mov_b32 s13, 0
	s_waitcnt lgkmcnt(0)
	v_pk_mul_f32 v[128:129], v[128:129], v[158:159] op_sel_hi:[1,0]
	v_pk_mul_f32 v[130:131], v[130:131], v[158:159] op_sel_hi:[1,0]
	v_pk_mul_f32 v[124:125], v[124:125], v[158:159] op_sel_hi:[1,0]
	v_pk_mul_f32 v[126:127], v[126:127], v[158:159] op_sel_hi:[1,0]
	v_pk_mul_f32 v[120:121], v[120:121], v[158:159] op_sel_hi:[1,0]
	v_pk_mul_f32 v[122:123], v[122:123], v[158:159] op_sel_hi:[1,0]
	v_pk_mul_f32 v[112:113], v[112:113], v[158:159] op_sel_hi:[1,0]
	v_pk_mul_f32 v[114:115], v[114:115], v[158:159] op_sel_hi:[1,0]
	v_cvt_pk_bf16_f32 v212, v120, v121
	v_cvt_pk_bf16_f32 v213, v122, v123
	v_cvt_pk_bf16_f32 v214, v112, v113
	v_cvt_pk_bf16_f32 v215, v114, v115
	v_cvt_pk_bf16_f32 v208, v128, v129
	v_cvt_pk_bf16_f32 v209, v130, v131
	v_cvt_pk_bf16_f32 v210, v124, v125
	v_cvt_pk_bf16_f32 v211, v126, v127
	v_cndmask_b32_dpp v216, v212, v208, vcc row_ror:8 row_mask:0xf bank_mask:0xf
	v_cndmask_b32_dpp v217, v213, v209, vcc row_ror:8 row_mask:0xf bank_mask:0xf
	v_cndmask_b32_dpp v218, v214, v210, vcc row_ror:8 row_mask:0xf bank_mask:0xf
	v_cndmask_b32_dpp v219, v215, v211, vcc row_ror:8 row_mask:0xf bank_mask:0xf
	s_not_b64 vcc, vcc
	v_cndmask_b32_dpp v220, v208, v212, vcc row_ror:8 row_mask:0xf bank_mask:0xf
	v_cndmask_b32_dpp v221, v209, v213, vcc row_ror:8 row_mask:0xf bank_mask:0xf
	v_cndmask_b32_dpp v222, v210, v214, vcc row_ror:8 row_mask:0xf bank_mask:0xf
	v_cndmask_b32_dpp v223, v211, v215, vcc row_ror:8 row_mask:0xf bank_mask:0xf
	s_not_b64 vcc, vcc
	global_store_dwordx4 v[178:179], v[216:219], off
	v_lshl_add_u64 v[178:179], v[178:179], 0, s[12:13]
	global_store_dwordx4 v[178:179], v[220:223], off
	v_lshl_add_u64 v[178:179], v[178:179], 0, s[12:13]
	v_pk_mul_f32 v[116:117], v[116:117], v[160:161] op_sel_hi:[1,0]
	v_pk_mul_f32 v[118:119], v[118:119], v[160:161] op_sel_hi:[1,0]
	v_pk_mul_f32 v[108:109], v[108:109], v[160:161] op_sel_hi:[1,0]
	v_pk_mul_f32 v[110:111], v[110:111], v[160:161] op_sel_hi:[1,0]
	v_pk_mul_f32 v[104:105], v[104:105], v[160:161] op_sel_hi:[1,0]
	v_pk_mul_f32 v[106:107], v[106:107], v[160:161] op_sel_hi:[1,0]
	v_pk_mul_f32 v[96:97], v[96:97], v[160:161] op_sel_hi:[1,0]
	v_pk_mul_f32 v[98:99], v[98:99], v[160:161] op_sel_hi:[1,0]
	v_cvt_pk_bf16_f32 v228, v104, v105
	v_cvt_pk_bf16_f32 v229, v106, v107
	v_cvt_pk_bf16_f32 v230, v96, v97
	v_cvt_pk_bf16_f32 v231, v98, v99
	v_cvt_pk_bf16_f32 v224, v116, v117
	v_cvt_pk_bf16_f32 v225, v118, v119
	v_cvt_pk_bf16_f32 v226, v108, v109
	v_cvt_pk_bf16_f32 v227, v110, v111
	v_cndmask_b32_dpp v232, v228, v224, vcc row_ror:8 row_mask:0xf bank_mask:0xf
	v_cndmask_b32_dpp v233, v229, v225, vcc row_ror:8 row_mask:0xf bank_mask:0xf
	v_cndmask_b32_dpp v234, v230, v226, vcc row_ror:8 row_mask:0xf bank_mask:0xf
	v_cndmask_b32_dpp v235, v231, v227, vcc row_ror:8 row_mask:0xf bank_mask:0xf
	s_not_b64 vcc, vcc
	v_cndmask_b32_dpp v236, v224, v228, vcc row_ror:8 row_mask:0xf bank_mask:0xf
	v_cndmask_b32_dpp v237, v225, v229, vcc row_ror:8 row_mask:0xf bank_mask:0xf
	v_cndmask_b32_dpp v238, v226, v230, vcc row_ror:8 row_mask:0xf bank_mask:0xf
	v_cndmask_b32_dpp v239, v227, v231, vcc row_ror:8 row_mask:0xf bank_mask:0xf
	s_not_b64 vcc, vcc
	global_store_dwordx4 v[178:179], v[232:235], off
	v_lshl_add_u64 v[178:179], v[178:179], 0, s[12:13]
	global_store_dwordx4 v[178:179], v[236:239], off
	v_lshl_add_u64 v[178:179], v[178:179], 0, s[12:13]
	v_pk_mul_f32 v[100:101], v[100:101], v[162:163] op_sel_hi:[1,0]
	v_pk_mul_f32 v[102:103], v[102:103], v[162:163] op_sel_hi:[1,0]
	v_pk_mul_f32 v[92:93], v[92:93], v[162:163] op_sel_hi:[1,0]
	v_pk_mul_f32 v[94:95], v[94:95], v[162:163] op_sel_hi:[1,0]
	v_pk_mul_f32 v[88:89], v[88:89], v[162:163] op_sel_hi:[1,0]
	v_pk_mul_f32 v[90:91], v[90:91], v[162:163] op_sel_hi:[1,0]
	v_pk_mul_f32 v[80:81], v[80:81], v[162:163] op_sel_hi:[1,0]
	v_pk_mul_f32 v[82:83], v[82:83], v[162:163] op_sel_hi:[1,0]
	v_cvt_pk_bf16_f32 v212, v88, v89
	v_cvt_pk_bf16_f32 v213, v90, v91
	v_cvt_pk_bf16_f32 v214, v80, v81
	v_cvt_pk_bf16_f32 v215, v82, v83
	v_cvt_pk_bf16_f32 v208, v100, v101
	v_cvt_pk_bf16_f32 v209, v102, v103
	v_cvt_pk_bf16_f32 v210, v92, v93
	v_cvt_pk_bf16_f32 v211, v94, v95
	v_cndmask_b32_dpp v216, v212, v208, vcc row_ror:8 row_mask:0xf bank_mask:0xf
	v_cndmask_b32_dpp v217, v213, v209, vcc row_ror:8 row_mask:0xf bank_mask:0xf
	v_cndmask_b32_dpp v218, v214, v210, vcc row_ror:8 row_mask:0xf bank_mask:0xf
	v_cndmask_b32_dpp v219, v215, v211, vcc row_ror:8 row_mask:0xf bank_mask:0xf
	s_not_b64 vcc, vcc
	v_cndmask_b32_dpp v220, v208, v212, vcc row_ror:8 row_mask:0xf bank_mask:0xf
	v_cndmask_b32_dpp v221, v209, v213, vcc row_ror:8 row_mask:0xf bank_mask:0xf
	v_cndmask_b32_dpp v222, v210, v214, vcc row_ror:8 row_mask:0xf bank_mask:0xf
	v_cndmask_b32_dpp v223, v211, v215, vcc row_ror:8 row_mask:0xf bank_mask:0xf
	s_not_b64 vcc, vcc
	global_store_dwordx4 v[178:179], v[216:219], off
	v_lshl_add_u64 v[178:179], v[178:179], 0, s[12:13]
	global_store_dwordx4 v[178:179], v[220:223], off
	v_lshl_add_u64 v[178:179], v[178:179], 0, s[12:13]
	v_pk_mul_f32 v[84:85], v[84:85], v[164:165] op_sel_hi:[1,0]
	v_pk_mul_f32 v[86:87], v[86:87], v[164:165] op_sel_hi:[1,0]
	v_pk_mul_f32 v[76:77], v[76:77], v[164:165] op_sel_hi:[1,0]
	v_pk_mul_f32 v[78:79], v[78:79], v[164:165] op_sel_hi:[1,0]
	v_pk_mul_f32 v[72:73], v[72:73], v[164:165] op_sel_hi:[1,0]
	v_pk_mul_f32 v[74:75], v[74:75], v[164:165] op_sel_hi:[1,0]
	v_pk_mul_f32 v[68:69], v[68:69], v[164:165] op_sel_hi:[1,0]
	v_pk_mul_f32 v[70:71], v[70:71], v[164:165] op_sel_hi:[1,0]
	v_cvt_pk_bf16_f32 v228, v72, v73
	v_cvt_pk_bf16_f32 v229, v74, v75
	v_cvt_pk_bf16_f32 v230, v68, v69
	v_cvt_pk_bf16_f32 v231, v70, v71
	v_cvt_pk_bf16_f32 v224, v84, v85
	v_cvt_pk_bf16_f32 v225, v86, v87
	v_cvt_pk_bf16_f32 v226, v76, v77
	v_cvt_pk_bf16_f32 v227, v78, v79
	v_cndmask_b32_dpp v232, v228, v224, vcc row_ror:8 row_mask:0xf bank_mask:0xf
	v_cndmask_b32_dpp v233, v229, v225, vcc row_ror:8 row_mask:0xf bank_mask:0xf
	v_cndmask_b32_dpp v234, v230, v226, vcc row_ror:8 row_mask:0xf bank_mask:0xf
	v_cndmask_b32_dpp v235, v231, v227, vcc row_ror:8 row_mask:0xf bank_mask:0xf
	s_not_b64 vcc, vcc
	v_cndmask_b32_dpp v236, v224, v228, vcc row_ror:8 row_mask:0xf bank_mask:0xf
	v_cndmask_b32_dpp v237, v225, v229, vcc row_ror:8 row_mask:0xf bank_mask:0xf
	v_cndmask_b32_dpp v238, v226, v230, vcc row_ror:8 row_mask:0xf bank_mask:0xf
	v_cndmask_b32_dpp v239, v227, v231, vcc row_ror:8 row_mask:0xf bank_mask:0xf
	s_not_b64 vcc, vcc
	global_store_dwordx4 v[178:179], v[232:235], off
	v_lshl_add_u64 v[178:179], v[178:179], 0, s[12:13]
	s_mov_b32 s12, 0x75000
	global_store_dwordx4 v[178:179], v[236:239], off
	v_lshl_add_u64 v[178:179], v[178:179], 0, s[12:13]
	s_mov_b32 s12, 0xd000
	v_pk_mul_f32 v[64:65], v[64:65], v[166:167] op_sel_hi:[1,0]
	v_pk_mul_f32 v[66:67], v[66:67], v[166:167] op_sel_hi:[1,0]
	v_pk_mul_f32 v[60:61], v[60:61], v[166:167] op_sel_hi:[1,0]
	v_pk_mul_f32 v[62:63], v[62:63], v[166:167] op_sel_hi:[1,0]
	v_pk_mul_f32 v[56:57], v[56:57], v[166:167] op_sel_hi:[1,0]
	v_pk_mul_f32 v[58:59], v[58:59], v[166:167] op_sel_hi:[1,0]
	v_pk_mul_f32 v[48:49], v[48:49], v[166:167] op_sel_hi:[1,0]
	v_pk_mul_f32 v[50:51], v[50:51], v[166:167] op_sel_hi:[1,0]
	v_cvt_pk_bf16_f32 v212, v56, v57
	v_cvt_pk_bf16_f32 v213, v58, v59
	v_cvt_pk_bf16_f32 v214, v48, v49
	v_cvt_pk_bf16_f32 v215, v50, v51
	v_cvt_pk_bf16_f32 v208, v64, v65
	v_cvt_pk_bf16_f32 v209, v66, v67
	v_cvt_pk_bf16_f32 v210, v60, v61
	v_cvt_pk_bf16_f32 v211, v62, v63
	v_cndmask_b32_dpp v216, v212, v208, vcc row_ror:8 row_mask:0xf bank_mask:0xf
	v_cndmask_b32_dpp v217, v213, v209, vcc row_ror:8 row_mask:0xf bank_mask:0xf
	v_cndmask_b32_dpp v218, v214, v210, vcc row_ror:8 row_mask:0xf bank_mask:0xf
	v_cndmask_b32_dpp v219, v215, v211, vcc row_ror:8 row_mask:0xf bank_mask:0xf
	s_not_b64 vcc, vcc
	v_cndmask_b32_dpp v220, v208, v212, vcc row_ror:8 row_mask:0xf bank_mask:0xf
	v_cndmask_b32_dpp v221, v209, v213, vcc row_ror:8 row_mask:0xf bank_mask:0xf
	v_cndmask_b32_dpp v222, v210, v214, vcc row_ror:8 row_mask:0xf bank_mask:0xf
	v_cndmask_b32_dpp v223, v211, v215, vcc row_ror:8 row_mask:0xf bank_mask:0xf
	s_not_b64 vcc, vcc
	global_store_dwordx4 v[178:179], v[216:219], off
	v_lshl_add_u64 v[178:179], v[178:179], 0, s[12:13]
	global_store_dwordx4 v[178:179], v[220:223], off
	v_lshl_add_u64 v[178:179], v[178:179], 0, s[12:13]
	v_pk_mul_f32 v[52:53], v[52:53], v[168:169] op_sel_hi:[1,0]
	v_pk_mul_f32 v[54:55], v[54:55], v[168:169] op_sel_hi:[1,0]
	v_pk_mul_f32 v[44:45], v[44:45], v[168:169] op_sel_hi:[1,0]
	v_pk_mul_f32 v[46:47], v[46:47], v[168:169] op_sel_hi:[1,0]
	v_pk_mul_f32 v[40:41], v[40:41], v[168:169] op_sel_hi:[1,0]
	v_pk_mul_f32 v[42:43], v[42:43], v[168:169] op_sel_hi:[1,0]
	v_pk_mul_f32 v[32:33], v[32:33], v[168:169] op_sel_hi:[1,0]
	v_pk_mul_f32 v[34:35], v[34:35], v[168:169] op_sel_hi:[1,0]
	v_cvt_pk_bf16_f32 v228, v40, v41
	v_cvt_pk_bf16_f32 v229, v42, v43
	v_cvt_pk_bf16_f32 v230, v32, v33
	v_cvt_pk_bf16_f32 v231, v34, v35
	v_cvt_pk_bf16_f32 v224, v52, v53
	v_cvt_pk_bf16_f32 v225, v54, v55
	v_cvt_pk_bf16_f32 v226, v44, v45
	v_cvt_pk_bf16_f32 v227, v46, v47
	v_cndmask_b32_dpp v232, v228, v224, vcc row_ror:8 row_mask:0xf bank_mask:0xf
	v_cndmask_b32_dpp v233, v229, v225, vcc row_ror:8 row_mask:0xf bank_mask:0xf
	v_cndmask_b32_dpp v234, v230, v226, vcc row_ror:8 row_mask:0xf bank_mask:0xf
	v_cndmask_b32_dpp v235, v231, v227, vcc row_ror:8 row_mask:0xf bank_mask:0xf
	s_not_b64 vcc, vcc
	v_cndmask_b32_dpp v236, v224, v228, vcc row_ror:8 row_mask:0xf bank_mask:0xf
	v_cndmask_b32_dpp v237, v225, v229, vcc row_ror:8 row_mask:0xf bank_mask:0xf
	v_cndmask_b32_dpp v238, v226, v230, vcc row_ror:8 row_mask:0xf bank_mask:0xf
	v_cndmask_b32_dpp v239, v227, v231, vcc row_ror:8 row_mask:0xf bank_mask:0xf
	s_not_b64 vcc, vcc
	global_store_dwordx4 v[178:179], v[232:235], off
	v_lshl_add_u64 v[178:179], v[178:179], 0, s[12:13]
	global_store_dwordx4 v[178:179], v[236:239], off
	v_lshl_add_u64 v[178:179], v[178:179], 0, s[12:13]
	v_pk_mul_f32 v[36:37], v[36:37], v[170:171] op_sel_hi:[1,0]
	v_pk_mul_f32 v[38:39], v[38:39], v[170:171] op_sel_hi:[1,0]
	v_pk_mul_f32 v[28:29], v[28:29], v[170:171] op_sel_hi:[1,0]
	v_pk_mul_f32 v[30:31], v[30:31], v[170:171] op_sel_hi:[1,0]
	v_pk_mul_f32 v[24:25], v[24:25], v[170:171] op_sel_hi:[1,0]
	v_pk_mul_f32 v[26:27], v[26:27], v[170:171] op_sel_hi:[1,0]
	v_pk_mul_f32 v[16:17], v[16:17], v[170:171] op_sel_hi:[1,0]
	v_pk_mul_f32 v[18:19], v[18:19], v[170:171] op_sel_hi:[1,0]
	v_cvt_pk_bf16_f32 v212, v24, v25
	v_cvt_pk_bf16_f32 v213, v26, v27
	v_cvt_pk_bf16_f32 v214, v16, v17
	v_cvt_pk_bf16_f32 v215, v18, v19
	v_cvt_pk_bf16_f32 v208, v36, v37
	v_cvt_pk_bf16_f32 v209, v38, v39
	v_cvt_pk_bf16_f32 v210, v28, v29
	v_cvt_pk_bf16_f32 v211, v30, v31
	v_cndmask_b32_dpp v216, v212, v208, vcc row_ror:8 row_mask:0xf bank_mask:0xf
	v_cndmask_b32_dpp v217, v213, v209, vcc row_ror:8 row_mask:0xf bank_mask:0xf
	v_cndmask_b32_dpp v218, v214, v210, vcc row_ror:8 row_mask:0xf bank_mask:0xf
	v_cndmask_b32_dpp v219, v215, v211, vcc row_ror:8 row_mask:0xf bank_mask:0xf
	s_not_b64 vcc, vcc
	v_cndmask_b32_dpp v220, v208, v212, vcc row_ror:8 row_mask:0xf bank_mask:0xf
	v_cndmask_b32_dpp v221, v209, v213, vcc row_ror:8 row_mask:0xf bank_mask:0xf
	v_cndmask_b32_dpp v222, v210, v214, vcc row_ror:8 row_mask:0xf bank_mask:0xf
	v_cndmask_b32_dpp v223, v211, v215, vcc row_ror:8 row_mask:0xf bank_mask:0xf
	s_not_b64 vcc, vcc
	global_store_dwordx4 v[178:179], v[216:219], off
	v_lshl_add_u64 v[178:179], v[178:179], 0, s[12:13]
	global_store_dwordx4 v[178:179], v[220:223], off
	v_lshl_add_u64 v[178:179], v[178:179], 0, s[12:13]
	v_pk_mul_f32 v[20:21], v[20:21], v[172:173] op_sel_hi:[1,0]
	v_pk_mul_f32 v[22:23], v[22:23], v[172:173] op_sel_hi:[1,0]
	v_pk_mul_f32 v[12:13], v[12:13], v[172:173] op_sel_hi:[1,0]
	v_pk_mul_f32 v[14:15], v[14:15], v[172:173] op_sel_hi:[1,0]
	v_pk_mul_f32 v[8:9], v[8:9], v[172:173] op_sel_hi:[1,0]
	v_pk_mul_f32 v[10:11], v[10:11], v[172:173] op_sel_hi:[1,0]
	v_pk_mul_f32 v[4:5], v[4:5], v[172:173] op_sel_hi:[1,0]
	v_pk_mul_f32 v[6:7], v[6:7], v[172:173] op_sel_hi:[1,0]
	v_cvt_pk_bf16_f32 v228, v8, v9
	v_cvt_pk_bf16_f32 v229, v10, v11
	v_cvt_pk_bf16_f32 v230, v4, v5
	v_cvt_pk_bf16_f32 v231, v6, v7
	v_cvt_pk_bf16_f32 v224, v20, v21
	v_cvt_pk_bf16_f32 v225, v22, v23
	v_cvt_pk_bf16_f32 v226, v12, v13
	v_cvt_pk_bf16_f32 v227, v14, v15
	v_cndmask_b32_dpp v232, v228, v224, vcc row_ror:8 row_mask:0xf bank_mask:0xf
	v_cndmask_b32_dpp v233, v229, v225, vcc row_ror:8 row_mask:0xf bank_mask:0xf
	v_cndmask_b32_dpp v234, v230, v226, vcc row_ror:8 row_mask:0xf bank_mask:0xf
	v_cndmask_b32_dpp v235, v231, v227, vcc row_ror:8 row_mask:0xf bank_mask:0xf
	s_not_b64 vcc, vcc
	v_cndmask_b32_dpp v236, v224, v228, vcc row_ror:8 row_mask:0xf bank_mask:0xf
	v_cndmask_b32_dpp v237, v225, v229, vcc row_ror:8 row_mask:0xf bank_mask:0xf
	v_cndmask_b32_dpp v238, v226, v230, vcc row_ror:8 row_mask:0xf bank_mask:0xf
	v_cndmask_b32_dpp v239, v227, v231, vcc row_ror:8 row_mask:0xf bank_mask:0xf
	s_not_b64 vcc, vcc
	global_store_dwordx4 v[178:179], v[232:235], off
	v_lshl_add_u64 v[178:179], v[178:179], 0, s[12:13]
	global_store_dwordx4 v[178:179], v[236:239], off
	s_andn2_b64 vcc, exec, s[38:39]
	s_mov_b64 s[16:17], -1
	s_cbranch_vccnz .LBB0_920
	s_andn2_b64 vcc, exec, s[0:1]
	s_cbranch_vccnz .LBB0_919
	s_barrier
	s_branch .LBB0_919
